# prep mod GEMV: silu(c) staging loop made straight-line with its 12 loads in flight and counted waits
# speedup vs baseline: 1.0215x; 1.0039x over previous
.LBB0_120:
	s_barrier
	s_and_saveexec_b64 s[20:21], s[0:1]
	s_cbranch_execz .LBB0_127
	v_lshlrev_b32_e32 v14, 2, v12
	v_add_u32_e32 v2, 0x1000, v14
	global_load_dword v88, v14, s[42:43]
	global_load_dword v89, v14, s[42:43] offset:1024
	global_load_dword v90, v14, s[42:43] offset:2048
	global_load_dword v91, v14, s[42:43] offset:3072
	global_load_dword v92, v14, s[56:57]
	global_load_dword v93, v14, s[56:57] offset:1024
	global_load_dword v94, v14, s[56:57] offset:2048
	global_load_dword v95, v14, s[56:57] offset:3072
	global_load_dword v96, v2, s[56:57]
	global_load_dword v97, v2, s[56:57] offset:1024
	global_load_dword v98, v2, s[56:57] offset:2048
	global_load_dword v99, v2, s[56:57] offset:3072
	s_waitcnt vmcnt(11)
	v_mul_f32_e32 v1, 0xbfb8aa3b, v88
	v_exp_f32_e32 v1, v1
	s_nop 0
	v_add_f32_e32 v1, 1.0, v1
	v_div_scale_f32 v4, s[24:25], v1, v1, 1.0
	v_rcp_f32_e32 v5, v4
	s_nop 0
	v_fma_f32 v6, -v4, v5, 1.0
	v_fmac_f32_e32 v5, v6, v5
	v_div_scale_f32 v6, vcc, 1.0, v1, 1.0
	v_mul_f32_e32 v7, v6, v5
	v_fma_f32 v8, -v4, v7, v6
	v_fmac_f32_e32 v7, v8, v5
	v_fma_f32 v4, -v4, v7, v6
	v_div_fmas_f32 v4, v4, v5, v7
	v_div_fixup_f32 v1, v4, v1, 1.0
	v_mul_f32_e32 v0, v88, v1
	ds_write_b32 v17, v0
	s_waitcnt vmcnt(10)
	v_mul_f32_e32 v1, 0xbfb8aa3b, v89
	v_exp_f32_e32 v1, v1
	s_nop 0
	v_add_f32_e32 v1, 1.0, v1
	v_div_scale_f32 v4, s[24:25], v1, v1, 1.0
	v_rcp_f32_e32 v5, v4
	s_nop 0
	v_fma_f32 v6, -v4, v5, 1.0
	v_fmac_f32_e32 v5, v6, v5
	v_div_scale_f32 v6, vcc, 1.0, v1, 1.0
	v_mul_f32_e32 v7, v6, v5
	v_fma_f32 v8, -v4, v7, v6
	v_fmac_f32_e32 v7, v8, v5
	v_fma_f32 v4, -v4, v7, v6
	v_div_fmas_f32 v4, v4, v5, v7
	v_div_fixup_f32 v1, v4, v1, 1.0
	v_mul_f32_e32 v0, v89, v1
	ds_write_b32 v17, v0 offset:1024
	s_waitcnt vmcnt(9)
	v_mul_f32_e32 v1, 0xbfb8aa3b, v90
	v_exp_f32_e32 v1, v1
	s_nop 0
	v_add_f32_e32 v1, 1.0, v1
	v_div_scale_f32 v4, s[24:25], v1, v1, 1.0
	v_rcp_f32_e32 v5, v4
	s_nop 0
	v_fma_f32 v6, -v4, v5, 1.0
	v_fmac_f32_e32 v5, v6, v5
	v_div_scale_f32 v6, vcc, 1.0, v1, 1.0
	v_mul_f32_e32 v7, v6, v5
	v_fma_f32 v8, -v4, v7, v6
	v_fmac_f32_e32 v7, v8, v5
	v_fma_f32 v4, -v4, v7, v6
	v_div_fmas_f32 v4, v4, v5, v7
	v_div_fixup_f32 v1, v4, v1, 1.0
	v_mul_f32_e32 v0, v90, v1
	ds_write_b32 v17, v0 offset:2048
	s_waitcnt vmcnt(8)
	v_mul_f32_e32 v1, 0xbfb8aa3b, v91
	v_exp_f32_e32 v1, v1
	s_nop 0
	v_add_f32_e32 v1, 1.0, v1
	v_div_scale_f32 v4, s[24:25], v1, v1, 1.0
	v_rcp_f32_e32 v5, v4
	s_nop 0
	v_fma_f32 v6, -v4, v5, 1.0
	v_fmac_f32_e32 v5, v6, v5
	v_div_scale_f32 v6, vcc, 1.0, v1, 1.0
	v_mul_f32_e32 v7, v6, v5
	v_fma_f32 v8, -v4, v7, v6
	v_fmac_f32_e32 v7, v8, v5
	v_fma_f32 v4, -v4, v7, v6
	v_div_fmas_f32 v4, v4, v5, v7
	v_div_fixup_f32 v1, v4, v1, 1.0
	v_mul_f32_e32 v0, v91, v1
	ds_write_b32 v17, v0 offset:3072
	s_waitcnt vmcnt(7)
	v_mul_f32_e32 v1, 0xbfb8aa3b, v92
	v_exp_f32_e32 v1, v1
	s_nop 0
	v_add_f32_e32 v1, 1.0, v1
	v_div_scale_f32 v4, s[24:25], v1, v1, 1.0
	v_rcp_f32_e32 v5, v4
	s_nop 0
	v_fma_f32 v6, -v4, v5, 1.0
	v_fmac_f32_e32 v5, v6, v5
	v_div_scale_f32 v6, vcc, 1.0, v1, 1.0
	v_mul_f32_e32 v7, v6, v5
	v_fma_f32 v8, -v4, v7, v6
	v_fmac_f32_e32 v7, v8, v5
	v_fma_f32 v4, -v4, v7, v6
	v_div_fmas_f32 v4, v4, v5, v7
	v_div_fixup_f32 v1, v4, v1, 1.0
	v_mul_f32_e32 v0, v92, v1
	ds_write_b32 v17, v0 offset:4096
	s_waitcnt vmcnt(6)
	v_mul_f32_e32 v1, 0xbfb8aa3b, v93
	v_exp_f32_e32 v1, v1
	s_nop 0
	v_add_f32_e32 v1, 1.0, v1
	v_div_scale_f32 v4, s[24:25], v1, v1, 1.0
	v_rcp_f32_e32 v5, v4
	s_nop 0
	v_fma_f32 v6, -v4, v5, 1.0
	v_fmac_f32_e32 v5, v6, v5
	v_div_scale_f32 v6, vcc, 1.0, v1, 1.0
	v_mul_f32_e32 v7, v6, v5
	v_fma_f32 v8, -v4, v7, v6
	v_fmac_f32_e32 v7, v8, v5
	v_fma_f32 v4, -v4, v7, v6
	v_div_fmas_f32 v4, v4, v5, v7
	v_div_fixup_f32 v1, v4, v1, 1.0
	v_mul_f32_e32 v0, v93, v1
	ds_write_b32 v17, v0 offset:5120
	s_waitcnt vmcnt(5)
	v_mul_f32_e32 v1, 0xbfb8aa3b, v94
	v_exp_f32_e32 v1, v1
	s_nop 0
	v_add_f32_e32 v1, 1.0, v1
	v_div_scale_f32 v4, s[24:25], v1, v1, 1.0
	v_rcp_f32_e32 v5, v4
	s_nop 0
	v_fma_f32 v6, -v4, v5, 1.0
	v_fmac_f32_e32 v5, v6, v5
	v_div_scale_f32 v6, vcc, 1.0, v1, 1.0
	v_mul_f32_e32 v7, v6, v5
	v_fma_f32 v8, -v4, v7, v6
	v_fmac_f32_e32 v7, v8, v5
	v_fma_f32 v4, -v4, v7, v6
	v_div_fmas_f32 v4, v4, v5, v7
	v_div_fixup_f32 v1, v4, v1, 1.0
	v_mul_f32_e32 v0, v94, v1
	ds_write_b32 v17, v0 offset:6144
	s_waitcnt vmcnt(4)
	v_mul_f32_e32 v1, 0xbfb8aa3b, v95
	v_exp_f32_e32 v1, v1
	s_nop 0
	v_add_f32_e32 v1, 1.0, v1
	v_div_scale_f32 v4, s[24:25], v1, v1, 1.0
	v_rcp_f32_e32 v5, v4
	s_nop 0
	v_fma_f32 v6, -v4, v5, 1.0
	v_fmac_f32_e32 v5, v6, v5
	v_div_scale_f32 v6, vcc, 1.0, v1, 1.0
	v_mul_f32_e32 v7, v6, v5
	v_fma_f32 v8, -v4, v7, v6
	v_fmac_f32_e32 v7, v8, v5
	v_fma_f32 v4, -v4, v7, v6
	v_div_fmas_f32 v4, v4, v5, v7
	v_div_fixup_f32 v1, v4, v1, 1.0
	v_mul_f32_e32 v0, v95, v1
	ds_write_b32 v17, v0 offset:7168
	s_waitcnt vmcnt(3)
	v_mul_f32_e32 v1, 0xbfb8aa3b, v96
	v_exp_f32_e32 v1, v1
	s_nop 0
	v_add_f32_e32 v1, 1.0, v1
	v_div_scale_f32 v4, s[24:25], v1, v1, 1.0
	v_rcp_f32_e32 v5, v4
	s_nop 0
	v_fma_f32 v6, -v4, v5, 1.0
	v_fmac_f32_e32 v5, v6, v5
	v_div_scale_f32 v6, vcc, 1.0, v1, 1.0
	v_mul_f32_e32 v7, v6, v5
	v_fma_f32 v8, -v4, v7, v6
	v_fmac_f32_e32 v7, v8, v5
	v_fma_f32 v4, -v4, v7, v6
	v_div_fmas_f32 v4, v4, v5, v7
	v_div_fixup_f32 v1, v4, v1, 1.0
	v_mul_f32_e32 v0, v96, v1
	ds_write_b32 v17, v0 offset:8192
	s_waitcnt vmcnt(2)
	v_mul_f32_e32 v1, 0xbfb8aa3b, v97
	v_exp_f32_e32 v1, v1
	s_nop 0
	v_add_f32_e32 v1, 1.0, v1
	v_div_scale_f32 v4, s[24:25], v1, v1, 1.0
	v_rcp_f32_e32 v5, v4
	s_nop 0
	v_fma_f32 v6, -v4, v5, 1.0
	v_fmac_f32_e32 v5, v6, v5
	v_div_scale_f32 v6, vcc, 1.0, v1, 1.0
	v_mul_f32_e32 v7, v6, v5
	v_fma_f32 v8, -v4, v7, v6
	v_fmac_f32_e32 v7, v8, v5
	v_fma_f32 v4, -v4, v7, v6
	v_div_fmas_f32 v4, v4, v5, v7
	v_div_fixup_f32 v1, v4, v1, 1.0
	v_mul_f32_e32 v0, v97, v1
	ds_write_b32 v17, v0 offset:9216
	s_waitcnt vmcnt(1)
	v_mul_f32_e32 v1, 0xbfb8aa3b, v98
	v_exp_f32_e32 v1, v1
	s_nop 0
	v_add_f32_e32 v1, 1.0, v1
	v_div_scale_f32 v4, s[24:25], v1, v1, 1.0
	v_rcp_f32_e32 v5, v4
	s_nop 0
	v_fma_f32 v6, -v4, v5, 1.0
	v_fmac_f32_e32 v5, v6, v5
	v_div_scale_f32 v6, vcc, 1.0, v1, 1.0
	v_mul_f32_e32 v7, v6, v5
	v_fma_f32 v8, -v4, v7, v6
	v_fmac_f32_e32 v7, v8, v5
	v_fma_f32 v4, -v4, v7, v6
	v_div_fmas_f32 v4, v4, v5, v7
	v_div_fixup_f32 v1, v4, v1, 1.0
	v_mul_f32_e32 v0, v98, v1
	ds_write_b32 v17, v0 offset:10240
	s_waitcnt vmcnt(0)
	v_mul_f32_e32 v1, 0xbfb8aa3b, v99
	v_exp_f32_e32 v1, v1
	s_nop 0
	v_add_f32_e32 v1, 1.0, v1
	v_div_scale_f32 v4, s[24:25], v1, v1, 1.0
	v_rcp_f32_e32 v5, v4
	s_nop 0
	v_fma_f32 v6, -v4, v5, 1.0
	v_fmac_f32_e32 v5, v6, v5
	v_div_scale_f32 v6, vcc, 1.0, v1, 1.0
	v_mul_f32_e32 v7, v6, v5
	v_fma_f32 v8, -v4, v7, v6
	v_fmac_f32_e32 v7, v8, v5
	v_fma_f32 v4, -v4, v7, v6
	v_div_fmas_f32 v4, v4, v5, v7
	v_div_fixup_f32 v1, v4, v1, 1.0
	v_mul_f32_e32 v0, v99, v1
	ds_write_b32 v17, v0 offset:11264
